# attn0: one static s_setprio 1 for waves 4-7 over the whole attention phase part
# speedup vs baseline: 1.0004x; 1.0004x over previous
.LBB0_431:
	v_writelane_b32 v255, s76, 19
	s_and_b32 s33, s7, -2
	v_writelane_b32 v255, s75, 20
	s_lshr_b32 s77, 0x80, s33
	s_lshl_b32 s75, s71, 10
	s_sub_i32 s76, 12, s33
	s_add_i32 s77, s77, -1
	s_add_i32 s75, s75, 0
	s_add_u32 s4, s0, 0x19000000
	s_addc_u32 s5, s1, 0
	v_writelane_b32 v255, s7, 21
	s_and_b64 s[2:3], exec, s[2:3]
	s_cselect_b32 s3, s83, s5
	v_writelane_b32 v255, s82, 22
	s_cselect_b32 s2, s82, s4
	s_add_u32 s4, s0, 0xb00000
	v_writelane_b32 v255, s83, 23
	v_writelane_b32 v255, s4, 24
	s_addc_u32 s4, s1, 0
	s_cmp_gt_i32 s71, 3
	v_lshlrev_b32_e32 v2, 1, v243
	v_lshrrev_b32_e32 v4, 5, v243
	s_cselect_b64 s[92:93], -1, 0
	s_lshl_b32 s6, s71, 4
	v_writelane_b32 v255, s4, 25
	v_and_b32_e32 v8, 8, v2
	v_lshlrev_b32_e32 v2, 3, v4
	v_lshlrev_b32_e32 v4, 4, v243
	v_mov_b32_e32 v5, v0
	s_ashr_i32 s7, s6, 31
	s_add_i32 s4, s6, 0x7fffffc0
	v_lshl_add_u64 v[6:7], s[2:3], 0, v[4:5]
	s_lshl_b32 s2, s71, 5
	v_writelane_b32 v255, s6, 26
	s_and_b32 s78, s2, 0x60
	s_lshl_b32 s78, s78, 5
	s_lshl_b32 s2, -1, s76
	v_writelane_b32 v255, s7, 27
	s_not_b32 s73, s2
	v_readlane_b32 s2, v255, 17
	v_lshrrev_b32_e32 v1, 1, v242
	s_and_b32 s4, s4, 0x7fffffe0
	v_mov_b32_e32 v3, v0
	v_readlane_b32 s3, v255, 18
	v_and_b32_e32 v150, 31, v242
	v_and_b32_e32 v1, 4, v1
	v_and_b32_e32 v9, 19, v242
	v_lshl_add_u64 v[116:117], v[6:7], 0, s[78:79]
	v_lshl_add_u64 v[118:119], s[2:3], 0, v[4:5]
	v_lshl_add_u64 v[120:121], s[18:19], 0, v[2:3]
	s_cmp_gt_i32 s10, 0
	v_or_b32_e32 v3, 2, v2
	v_or_b32_e32 v4, 3, v2
	v_or_b32_e32 v5, 4, v2
	v_or_b32_e32 v6, 5, v2
	v_or_b32_e32 v7, 6, v2
	v_or_b32_e32 v10, 7, v2
	v_or_b32_e32 v11, 16, v2
	s_waitcnt lgkmcnt(3)
	v_or_b32_e32 v12, 17, v2
	s_waitcnt lgkmcnt(2)
	v_or_b32_e32 v13, 18, v2
	s_waitcnt lgkmcnt(0)
	v_or_b32_e32 v14, 19, v2
	v_or_b32_e32 v15, 20, v2
	v_or_b32_e32 v16, 21, v2
	v_or_b32_e32 v17, 22, v2
	v_or_b32_e32 v18, 23, v2
	v_or_b32_e32 v19, 1, v2
	v_or_b32_e32 v151, s4, v150
	v_writelane_b32 v255, s10, 28
	s_cselect_b64 s[88:89], -1, 0
	v_lshl_add_u32 v152, v243, 4, 0
	v_cmp_gt_u32_e64 s[2:3], 32, v243
	v_cmp_gt_u32_e64 s[4:5], v2, v150
	v_cmp_lt_u32_e64 s[6:7], v2, v150
	v_cmp_gt_u32_e64 s[8:9], v3, v150
	v_cmp_gt_u32_e64 s[10:11], v4, v150
	v_cmp_gt_u32_e64 s[12:13], v5, v150
	v_cmp_gt_u32_e64 s[14:15], v6, v150
	v_cmp_gt_u32_e64 s[16:17], v7, v150
	v_cmp_gt_u32_e64 s[18:19], v10, v150
	v_cmp_gt_u32_e64 s[20:21], v11, v150
	v_cmp_gt_u32_e64 s[22:23], v12, v150
	v_cmp_gt_u32_e64 s[24:25], v13, v150
	v_cmp_gt_u32_e64 s[26:27], v14, v150
	v_cmp_gt_u32_e64 s[28:29], v15, v150
	v_cmp_gt_u32_e64 s[30:31], v16, v150
	v_cmp_gt_u32_e64 s[34:35], v17, v150
	v_cmp_gt_u32_e64 s[36:37], v18, v150
	v_cmp_lt_u32_e64 s[38:39], v19, v150
	v_cmp_lt_u32_e64 s[40:41], v3, v150
	v_cmp_lt_u32_e64 s[42:43], v4, v150
	v_cmp_lt_u32_e64 s[44:45], v5, v150
	v_cmp_lt_u32_e64 s[46:47], v6, v150
	v_cmp_lt_u32_e64 s[48:49], v7, v150
	v_cmp_lt_u32_e64 s[50:51], v10, v150
	v_cmp_lt_u32_e64 s[52:53], v11, v150
	v_cmp_lt_u32_e64 s[54:55], v12, v150
	v_cmp_lt_u32_e64 s[56:57], v13, v150
	v_cmp_lt_u32_e64 s[58:59], v14, v150
	v_cmp_lt_u32_e64 s[60:61], v15, v150
	v_cmp_lt_u32_e64 s[62:63], v16, v150
	v_cmp_lt_u32_e64 s[64:65], v17, v150
	v_cmp_lt_u32_e64 s[66:67], v18, v150
	v_or3_b32 v153, v1, v9, v8
	s_lshl_b32 s86, s70, 6
	v_lshlrev_b32_e32 v122, 1, v2
	s_cmp_lt_u32 s71, 4
	s_cbranch_scc1 .La0_nopr
	s_setprio 1
.La0_nopr:
	s_branch .LBB0_433
.LBB0_432:
	v_readlane_b32 s68, v254, 0
	s_add_i32 s70, s70, s68
	v_readlane_b32 s68, v255, 3
	s_add_i32 s86, s86, s68
	s_cmpk_gt_i32 s70, 0xff
	v_readlane_b32 s69, v254, 1
	s_cbranch_scc1 .LBB0_486

.LBB0_486:
	s_setprio 0
	v_readlane_b32 s82, v255, 22
	v_readlane_b32 s92, v255, 10
	v_readlane_b32 s72, v254, 10
	v_readlane_b32 s62, v255, 13
	v_readlane_b32 s63, v255, 14
	s_mov_b32 s64, 0xf800000
	v_readlane_b32 s65, v255, 15
	s_mov_b32 s66, 0xbfb8aa3b
	s_mov_b32 s67, 0x1fffe0
	s_movk_i32 s68, 0xb00
	s_movk_i32 s69, 0x1600
	s_movk_i32 s73, 0x161
	v_readlane_b32 s74, v255, 16
	v_readlane_b32 s75, v255, 20
	v_readlane_b32 s76, v255, 19
	v_readlane_b32 s83, v255, 23
	v_readlane_b32 s10, v255, 28
	v_readlane_b32 s7, v255, 21
